# simplified per-unit StaticOrder::next (group size is always 8: shift/mask instead of the generic rcp-based division) in all 8 GEMM unit-loop headers
# speedup vs baseline: 1.0224x; 1.0018x over previous
;     __host__ __device__ bool next(int i, Unit& u) const {
;         const long L = (long)i * G + c; if (L >= nwg) return false;
;         int wgid = (int)L; { const int q = nwg / NXCD, r = nwg % NXCD, xcd = wgid % NXCD, off = wgid / NXCD; wgid = (xcd < r ? xcd * (q + 1) : r * (q + 1) + (xcd - r) * q) + off; }
;         const int nig = WGM * nN, gid = wgid / nig, fm = gid * WGM, gsz = (nM - fm) < WGM ? (nM - fm) : WGM;
;         u.pm = fm + ((wgid % nig) % gsz); u.pn = (wgid % nig) / gsz; return true;
;     }
.LBB0_348:
	s_add_i32 s79, s79, 1
	s_mul_i32 s0, s79, s73
	s_mul_hi_u32 s1, s79, s83
	s_add_i32 s1, s1, s0
	s_mul_i32 s0, s79, s83
	s_add_u32 s2, s0, s86
	s_addc_u32 s3, s1, s74
	v_cmp_gt_i64_e32 vcc, s[2:3], v[144:145]
	v_cmp_lt_i64_e64 s[0:1], s[2:3], v[142:143]
	s_cbranch_vccnz .LBB0_350
	s_ashr_i32 s3, s2, 31
	s_lshr_b32 s3, s3, 29
	s_add_i32 s3, s2, s3
	s_ashr_i32 s11, s3, 3
	s_and_b32 s3, s3, -8
	s_sub_i32 s2, s2, s3
	s_cmp_lt_i32 s2, 0
	s_movk_i32 s3, 0x171
	s_cselect_b32 s3, s3, 0x170
	s_mul_i32 s2, s2, s3
	s_add_i32 s2, s2, s11
	s_mul_hi_i32 s3, s2, 0xb21642c9
	s_add_i32 s3, s3, s2
	s_lshr_b32 s11, s3, 31
	s_ashr_i32 s3, s3, 7
	s_add_i32 s3, s3, s11
	s_lshl_b32 s11, s3, 3
	s_mulk_i32 s3, 0xb8
	s_sub_i32 s2, s2, s3
	s_lshr_b32 s80, s2, 3
	s_and_b32 s2, s2, 7
	s_add_i32 s81, s11, s2
	s_add_i32 s80, s80, s32
	s_sub_i32 s2, s80, 23
	s_cmp_ge_i32 s80, 23
	s_cselect_b32 s80, s2, s80

;     __host__ __device__ bool next(int i, Unit& u) const {
;         const long L = (long)i * G + c; if (L >= nwg) return false;
;         int wgid = (int)L; { const int q = nwg / NXCD, r = nwg % NXCD, xcd = wgid % NXCD, off = wgid / NXCD; wgid = (xcd < r ? xcd * (q + 1) : r * (q + 1) + (xcd - r) * q) + off; }
;         const int nig = WGM * nN, gid = wgid / nig, fm = gid * WGM, gsz = (nM - fm) < WGM ? (nM - fm) : WGM;
;         u.pm = fm + ((wgid % nig) % gsz); u.pn = (wgid % nig) / gsz; return true;
;     }
.LBB0_705:
	s_ashr_i32 s4, s28, 3
	s_add_i32 s4, s56, s4
	s_ashr_i32 s5, s4, 31
	s_lshr_b32 s5, s5, 26
	s_add_i32 s5, s4, s5
	s_ashr_i32 s28, s5, 6
	s_lshl_b32 s28, s28, 3
	s_andn2_b32 s5, s5, 63
	s_sub_i32 s4, s4, s5
	s_lshr_b32 s56, s4, 3
	s_and_b32 s4, s4, 7
	s_add_i32 s57, s28, s4

;     __host__ __device__ bool next(int i, Unit& u) const {
;         const long L = (long)i * G + c; if (L >= nwg) return false;
;         int wgid = (int)L; { const int q = nwg / NXCD, r = nwg % NXCD, xcd = wgid % NXCD, off = wgid / NXCD; wgid = (xcd < r ? xcd * (q + 1) : r * (q + 1) + (xcd - r) * q) + off; }
;         const int nig = WGM * nN, gid = wgid / nig, fm = gid * WGM, gsz = (nM - fm) < WGM ? (nM - fm) : WGM;
;         u.pm = fm + ((wgid % nig) % gsz); u.pn = (wgid % nig) / gsz; return true;
;     }
.LBB0_768:
	s_ashr_i32 s2, s28, 3
	s_add_i32 s2, s52, s2
	s_ashr_i32 s3, s2, 31
	s_lshr_b32 s3, s3, 26
	s_add_i32 s3, s2, s3
	s_ashr_i32 s28, s3, 6
	s_lshl_b32 s28, s28, 3
	s_andn2_b32 s3, s3, 63
	s_sub_i32 s2, s2, s3
	s_lshr_b32 s52, s2, 3
	s_and_b32 s2, s2, 7
	s_add_i32 s53, s28, s2

;     __host__ __device__ bool next(int i, Unit& u) const {
;         const long L = (long)i * G + c; if (L >= nwg) return false;
;         int wgid = (int)L; { const int q = nwg / NXCD, r = nwg % NXCD, xcd = wgid % NXCD, off = wgid / NXCD; wgid = (xcd < r ? xcd * (q + 1) : r * (q + 1) + (xcd - r) * q) + off; }
;         const int nig = WGM * nN, gid = wgid / nig, fm = gid * WGM, gsz = (nM - fm) < WGM ? (nM - fm) : WGM;
;         u.pm = fm + ((wgid % nig) % gsz); u.pn = (wgid % nig) / gsz; return true;
;     }
.LBB0_833:
	s_ashr_i32 s4, s30, 3
	s_add_i32 s4, s54, s4
	s_ashr_i32 s5, s4, 31
	s_lshr_b32 s5, s5, 26
	s_add_i32 s5, s4, s5
	s_ashr_i32 s30, s5, 6
	s_lshl_b32 s30, s30, 3
	s_andn2_b32 s5, s5, 63
	s_sub_i32 s4, s4, s5
	s_lshr_b32 s54, s4, 3
	s_and_b32 s4, s4, 7
	s_add_i32 s55, s30, s4

;     __host__ __device__ bool next(int i, Unit& u) const {
;         const long L = (long)i * G + c; if (L >= nwg) return false;
;         int wgid = (int)L; { const int q = nwg / NXCD, r = nwg % NXCD, xcd = wgid % NXCD, off = wgid / NXCD; wgid = (xcd < r ? xcd * (q + 1) : r * (q + 1) + (xcd - r) * q) + off; }
;         const int nig = WGM * nN, gid = wgid / nig, fm = gid * WGM, gsz = (nM - fm) < WGM ? (nM - fm) : WGM;
;         u.pm = fm + ((wgid % nig) % gsz); u.pn = (wgid % nig) / gsz; return true;
;     }
.LBB0_896:
	s_ashr_i32 s2, s26, 3
	s_add_i32 s2, s54, s2
	s_ashr_i32 s3, s2, 31
	s_lshr_b32 s3, s3, 26
	s_add_i32 s3, s2, s3
	s_ashr_i32 s26, s3, 6
	s_lshl_b32 s26, s26, 3
	s_andn2_b32 s3, s3, 63
	s_sub_i32 s2, s2, s3
	s_lshr_b32 s54, s2, 3
	s_and_b32 s2, s2, 7
	s_add_i32 s55, s26, s2

;     __host__ __device__ bool next(int i, Unit& u) const {
;         const long L = (long)i * G + c; if (L >= nwg) return false;
;         int wgid = (int)L; { const int q = nwg / NXCD, r = nwg % NXCD, xcd = wgid % NXCD, off = wgid / NXCD; wgid = (xcd < r ? xcd * (q + 1) : r * (q + 1) + (xcd - r) * q) + off; }
;         const int nig = WGM * nN, gid = wgid / nig, fm = gid * WGM, gsz = (nM - fm) < WGM ? (nM - fm) : WGM;
;         u.pm = fm + ((wgid % nig) % gsz); u.pn = (wgid % nig) / gsz; return true;
;     }
.LBB0_1002:
	s_add_i32 s41, s41, 1
	s_mul_i32 s0, s41, s49
	s_mul_hi_u32 s1, s41, s83
	s_add_i32 s1, s1, s0
	s_mul_i32 s0, s41, s83
	s_add_u32 s2, s0, s80
	s_addc_u32 s3, s1, s50
	v_cmp_gt_i64_e32 vcc, s[2:3], v[176:177]
	v_cmp_lt_i64_e64 s[0:1], s[2:3], v[174:175]
	s_cbranch_vccnz .LBB0_1004
	s_ashr_i32 s3, s2, 31
	s_lshr_b32 s3, s3, 29
	s_add_i32 s3, s2, s3
	s_ashr_i32 s11, s3, 3
	s_and_b32 s3, s3, -8
	s_sub_i32 s2, s2, s3
	s_cmp_lt_i32 s2, 0
	s_cselect_b32 s3, s51, 0x60
	s_mul_i32 s2, s2, s3
	s_add_i32 s2, s2, s11
	s_mul_hi_i32 s3, s2, 0x2aaaaaab
	s_lshr_b32 s11, s3, 31
	s_ashr_i32 s3, s3, 3
	s_add_i32 s3, s3, s11
	s_lshl_b32 s11, s3, 3
	s_mul_i32 s3, s3, 48
	s_sub_i32 s2, s2, s3
	s_lshr_b32 s33, s2, 3
	s_and_b32 s2, s2, 7
	s_add_i32 s55, s11, s2

;     __host__ __device__ bool next(int i, Unit& u) const {
;         const long L = (long)i * G + c; if (L >= nwg) return false;
;         int wgid = (int)L; { const int q = nwg / NXCD, r = nwg % NXCD, xcd = wgid % NXCD, off = wgid / NXCD; wgid = (xcd < r ? xcd * (q + 1) : r * (q + 1) + (xcd - r) * q) + off; }
;         const int nig = WGM * nN, gid = wgid / nig, fm = gid * WGM, gsz = (nM - fm) < WGM ? (nM - fm) : WGM;
;         u.pm = fm + ((wgid % nig) % gsz); u.pn = (wgid % nig) / gsz; return true;
;     }
.LBB0_1304:
	s_ashr_i32 s2, s18, 3
	s_add_i32 s2, s22, s2
	s_ashr_i32 s3, s2, 31
	s_lshr_b32 s3, s3, 27
	s_add_i32 s3, s2, s3
	s_ashr_i32 s18, s3, 5
	s_lshl_b32 s18, s18, 3
	s_andn2_b32 s3, s3, 31
	s_sub_i32 s2, s2, s3
	s_lshr_b32 s54, s2, 3
	s_and_b32 s2, s2, 7
	s_add_i32 s55, s18, s2

;     __host__ __device__ bool next(int i, Unit& u) const {
;         const long L = (long)i * G + c; if (L >= nwg) return false;
;         int wgid = (int)L; { const int q = nwg / NXCD, r = nwg % NXCD, xcd = wgid % NXCD, off = wgid / NXCD; wgid = (xcd < r ? xcd * (q + 1) : r * (q + 1) + (xcd - r) * q) + off; }
;         const int nig = WGM * nN, gid = wgid / nig, fm = gid * WGM, gsz = (nM - fm) < WGM ? (nM - fm) : WGM;
;         u.pm = fm + ((wgid % nig) % gsz); u.pn = (wgid % nig) / gsz; return true;
;     }
.LBB0_1390:
	s_ashr_i32 s2, s18, 3
	s_add_i32 s2, s47, s2
	s_ashr_i32 s3, s2, 31
	s_lshr_b32 s3, s3, 27
	s_add_i32 s3, s2, s3
	s_ashr_i32 s18, s3, 5
	s_lshl_b32 s18, s18, 3
	s_andn2_b32 s3, s3, 31
	s_sub_i32 s2, s2, s3
	s_lshr_b32 s47, s2, 3
	s_and_b32 s2, s2, 7
	s_add_i32 s48, s18, s2
